# stack + hyena data/combine loops: 4 halo loads per trip issued together under lane masks, one wait
# speedup vs baseline: 1.0137x; 1.0110x over previous
.LBB0_991:
	v_lshl_add_u64 v[8:9], s[78:79], 0, v[2:3]
	v_add_co_u32_e32 v6, vcc, 0x2500000, v8
	v_cmp_lt_i32_e64 s[0:1], 0, v0
	s_nop 0
	v_addc_co_u32_e32 v7, vcc, 0, v9, vcc
	global_load_dwordx2 v[6:7], v[6:7], off offset:512
	v_mov_b32_e32 v166, 0
	v_mov_b32_e32 v167, 0
	v_mov_b32_e32 v168, 0
	v_mov_b32_e32 v169, 0
	s_movk_i32 s4, 0x3ffc
	v_cmp_gt_i32_e64 s[4:5], s4, v0
	v_lshl_add_u64 v[170:171], v[0:1], 1, s[18:19]
	v_add_co_u32_e32 v172, vcc, 0x2500000, v8
	s_nop 1
	v_addc_co_u32_e32 v173, vcc, 0, v9, vcc
	v_lshl_add_u64 v[174:175], v[0:1], 1, s[20:21]
	v_add_co_u32_e32 v176, vcc, 0x55c0000, v8
	s_nop 1
	v_addc_co_u32_e32 v177, vcc, 0, v9, vcc
	global_load_dwordx2 v[10:11], v[176:177], off offset:512
	s_mov_b64 s[26:27], exec
	s_and_b64 exec, s[26:27], s[0:1]
	global_load_ushort v166, v[170:171], off offset:510
	global_load_ushort v168, v[174:175], off offset:-2
	s_and_b64 exec, s[26:27], s[4:5]
	global_load_ushort v167, v[172:173], off offset:520
	global_load_ushort v169, v[176:177], off offset:520
	s_mov_b64 exec, s[26:27]
	s_waitcnt vmcnt(0)
	v_lshlrev_b32_e32 v18, 16, v166
	v_lshlrev_b32_e32 v17, 16, v167
	v_lshlrev_b32_e32 v20, 16, v168
	v_lshlrev_b32_e32 v19, 16, v169
	s_branch .LBB0_990

.LBB0_1078:
	v_readlane_b32 s64, v251, 2
	v_readlane_b32 s78, v251, 16
	v_readlane_b32 s79, v251, 17
	s_mov_b64 s[0:1], 0x16a00000
	v_mov_b32_e32 v42, 0
	v_lshl_add_u64 v[36:37], s[78:79], 0, v[34:35]
	v_add_co_u32_e32 v4, vcc, 0x16a00000, v36
	v_lshl_add_u64 v[2:3], v[36:37], 0, s[0:1]
	s_nop 0
	v_addc_co_u32_e32 v5, vcc, 0, v37, vcc
	v_add_co_u32_e32 v6, vcc, 0x16a20000, v36
	s_mov_b64 s[0:1], 0x16a20000
	s_nop 0
	v_addc_co_u32_e32 v7, vcc, 0, v37, vcc
	v_lshl_add_u64 v[46:47], s[78:79], 0, v[32:33]
	v_lshl_add_u64 v[38:39], v[36:37], 0, s[0:1]
	global_load_dwordx4 v[18:21], v[4:5], off
	global_load_dwordx4 v[14:17], v[6:7], off
	s_nop 0
	global_load_dwordx4 v[6:9], v[2:3], off offset:16
	s_nop 0
	global_load_dwordx4 v[2:5], v[38:39], off offset:16
	v_add_co_u32_e32 v10, vcc, 0x2500000, v46
	v_cmp_lt_i32_e64 s[0:1], 0, v0
	s_nop 0
	v_addc_co_u32_e32 v11, vcc, 0, v47, vcc
	global_load_dwordx2 v[40:41], v[10:11], off offset:512
	ds_read_b128 v[22:25], v50
	ds_read_b128 v[10:13], v50 offset:16
	v_mov_b32_e32 v51, 0
	v_readlane_b32 s65, v251, 3
	v_readlane_b32 s66, v251, 4
	v_readlane_b32 s67, v251, 5
	v_readlane_b32 s68, v251, 6
	v_readlane_b32 s69, v251, 7
	v_readlane_b32 s70, v251, 8
	v_readlane_b32 s71, v251, 9
	v_readlane_b32 s72, v251, 10
	v_readlane_b32 s73, v251, 11
	v_readlane_b32 s74, v251, 12
	v_readlane_b32 s75, v251, 13
	v_readlane_b32 s76, v251, 14
	v_readlane_b32 s77, v251, 15
	v_mov_b32_e32 v166, 0
	v_mov_b32_e32 v167, 0
	v_mov_b32_e32 v168, 0
	v_mov_b32_e32 v169, 0
	s_movk_i32 s4, 0x3ffc
	v_cmp_gt_i32_e64 s[4:5], s4, v0
	v_lshl_add_u64 v[170:171], v[0:1], 1, s[26:27]
	v_add_co_u32_e32 v172, vcc, 0x2500000, v46
	s_nop 1
	v_addc_co_u32_e32 v173, vcc, 0, v47, vcc
	v_lshl_add_u64 v[174:175], v[0:1], 1, s[28:29]
	v_add_co_u32_e32 v176, vcc, 0x55c0000, v46
	s_nop 1
	v_addc_co_u32_e32 v177, vcc, 0, v47, vcc
	global_load_dwordx2 v[44:45], v[176:177], off offset:512
	s_mov_b64 s[30:31], exec
	s_and_b64 exec, s[30:31], s[0:1]
	global_load_ushort v166, v[170:171], off offset:510
	global_load_ushort v168, v[174:175], off offset:-2
	s_and_b64 exec, s[30:31], s[4:5]
	global_load_ushort v167, v[172:173], off offset:520
	global_load_ushort v169, v[176:177], off offset:520
	s_mov_b64 exec, s[30:31]
	s_waitcnt vmcnt(0)
	v_lshlrev_b32_e32 v51, 16, v166
	v_lshlrev_b32_e32 v42, 16, v167
	v_lshlrev_b32_e32 v52, 16, v168
	v_lshlrev_b32_e32 v43, 16, v169
